# final RMSNorm routines: X2 loads without the non-temporal hint (stores keep it)
# baseline (speedup 1.0000x reference)
.Lp10a_loop:
	s_add_u32 s8, s12, 0x1000
	s_addc_u32 s9, s13, 0
	global_load_dwordx2 v[20:21], v1, s[12:13]
	global_load_dwordx2 v[22:23], v1, s[12:13] offset:512
	global_load_dwordx2 v[24:25], v1, s[12:13] offset:1024
	global_load_dwordx2 v[26:27], v1, s[12:13] offset:1536
	global_load_dwordx2 v[28:29], v1, s[12:13] offset:2048
	global_load_dwordx2 v[30:31], v1, s[12:13] offset:2560
	global_load_dwordx2 v[32:33], v1, s[12:13] offset:3072
	global_load_dwordx2 v[34:35], v1, s[12:13] offset:3584
	global_load_dwordx2 v[36:37], v1, s[8:9]
	global_load_dwordx2 v[38:39], v1, s[8:9] offset:512
	global_load_dwordx2 v[40:41], v1, s[8:9] offset:1024
	global_load_dwordx2 v[42:43], v1, s[8:9] offset:1536
	global_load_dwordx2 v[44:45], v1, s[8:9] offset:2048
	global_load_dwordx2 v[46:47], v1, s[8:9] offset:2560
	global_load_dwordx2 v[48:49], v1, s[8:9] offset:3072
	global_load_dwordx2 v[50:51], v1, s[8:9] offset:3584
	s_waitcnt vmcnt(0)
	v_lshlrev_b32_e32 v52, 16, v20
	v_and_b32_e32 v53, 0xffff0000, v20
	v_lshlrev_b32_e32 v54, 16, v21
	v_and_b32_e32 v55, 0xffff0000, v21
	v_lshlrev_b32_e32 v56, 16, v22
	v_and_b32_e32 v57, 0xffff0000, v22
	v_lshlrev_b32_e32 v58, 16, v23
	v_and_b32_e32 v59, 0xffff0000, v23
	v_lshlrev_b32_e32 v60, 16, v24
	v_and_b32_e32 v61, 0xffff0000, v24
	v_lshlrev_b32_e32 v62, 16, v25
	v_and_b32_e32 v63, 0xffff0000, v25
	v_lshlrev_b32_e32 v64, 16, v26
	v_and_b32_e32 v65, 0xffff0000, v26
	v_lshlrev_b32_e32 v66, 16, v27
	v_and_b32_e32 v67, 0xffff0000, v27
	v_lshlrev_b32_e32 v68, 16, v28
	v_and_b32_e32 v69, 0xffff0000, v28
	v_lshlrev_b32_e32 v70, 16, v29
	v_and_b32_e32 v71, 0xffff0000, v29
	v_lshlrev_b32_e32 v72, 16, v30
	v_and_b32_e32 v73, 0xffff0000, v30
	v_lshlrev_b32_e32 v74, 16, v31
	v_and_b32_e32 v75, 0xffff0000, v31
	v_lshlrev_b32_e32 v76, 16, v32
	v_and_b32_e32 v77, 0xffff0000, v32
	v_lshlrev_b32_e32 v78, 16, v33
	v_and_b32_e32 v79, 0xffff0000, v33
	v_lshlrev_b32_e32 v80, 16, v34
	v_and_b32_e32 v81, 0xffff0000, v34
	v_lshlrev_b32_e32 v82, 16, v35
	v_and_b32_e32 v83, 0xffff0000, v35
	v_lshlrev_b32_e32 v84, 16, v36
	v_and_b32_e32 v85, 0xffff0000, v36
	v_lshlrev_b32_e32 v86, 16, v37
	v_and_b32_e32 v87, 0xffff0000, v37
	v_lshlrev_b32_e32 v88, 16, v38
	v_and_b32_e32 v89, 0xffff0000, v38
	v_lshlrev_b32_e32 v90, 16, v39
	v_and_b32_e32 v91, 0xffff0000, v39
	v_lshlrev_b32_e32 v92, 16, v40
	v_and_b32_e32 v93, 0xffff0000, v40
	v_lshlrev_b32_e32 v94, 16, v41
	v_and_b32_e32 v95, 0xffff0000, v41
	v_lshlrev_b32_e32 v96, 16, v42
	v_and_b32_e32 v97, 0xffff0000, v42
	v_lshlrev_b32_e32 v98, 16, v43
	v_and_b32_e32 v99, 0xffff0000, v43
	v_lshlrev_b32_e32 v100, 16, v44
	v_and_b32_e32 v101, 0xffff0000, v44
	v_lshlrev_b32_e32 v102, 16, v45
	v_and_b32_e32 v103, 0xffff0000, v45
	v_lshlrev_b32_e32 v104, 16, v46
	v_and_b32_e32 v105, 0xffff0000, v46
	v_lshlrev_b32_e32 v106, 16, v47
	v_and_b32_e32 v107, 0xffff0000, v47
	v_lshlrev_b32_e32 v108, 16, v48
	v_and_b32_e32 v109, 0xffff0000, v48
	v_lshlrev_b32_e32 v110, 16, v49
	v_and_b32_e32 v111, 0xffff0000, v49
	v_lshlrev_b32_e32 v112, 16, v50
	v_and_b32_e32 v113, 0xffff0000, v50
	v_lshlrev_b32_e32 v114, 16, v51
	v_and_b32_e32 v115, 0xffff0000, v51
	v_mul_f32_e32 v116, v52, v52
	v_mul_f32_e32 v117, v68, v68
	v_mul_f32_e32 v118, v84, v84
	v_mul_f32_e32 v119, v100, v100
	v_fmac_f32_e32 v116, v53, v53
	v_fmac_f32_e32 v117, v69, v69
	v_fmac_f32_e32 v118, v85, v85
	v_fmac_f32_e32 v119, v101, v101
	v_fmac_f32_e32 v116, v54, v54
	v_fmac_f32_e32 v117, v70, v70
	v_fmac_f32_e32 v118, v86, v86
	v_fmac_f32_e32 v119, v102, v102
	v_fmac_f32_e32 v116, v55, v55
	v_fmac_f32_e32 v117, v71, v71
	v_fmac_f32_e32 v118, v87, v87
	v_fmac_f32_e32 v119, v103, v103
	v_fmac_f32_e32 v116, v56, v56
	v_fmac_f32_e32 v117, v72, v72
	v_fmac_f32_e32 v118, v88, v88
	v_fmac_f32_e32 v119, v104, v104
	v_fmac_f32_e32 v116, v57, v57
	v_fmac_f32_e32 v117, v73, v73
	v_fmac_f32_e32 v118, v89, v89
	v_fmac_f32_e32 v119, v105, v105
	v_fmac_f32_e32 v116, v58, v58
	v_fmac_f32_e32 v117, v74, v74
	v_fmac_f32_e32 v118, v90, v90
	v_fmac_f32_e32 v119, v106, v106
	v_fmac_f32_e32 v116, v59, v59
	v_fmac_f32_e32 v117, v75, v75
	v_fmac_f32_e32 v118, v91, v91
	v_fmac_f32_e32 v119, v107, v107
	v_fmac_f32_e32 v116, v60, v60
	v_fmac_f32_e32 v117, v76, v76
	v_fmac_f32_e32 v118, v92, v92
	v_fmac_f32_e32 v119, v108, v108
	v_fmac_f32_e32 v116, v61, v61
	v_fmac_f32_e32 v117, v77, v77
	v_fmac_f32_e32 v118, v93, v93
	v_fmac_f32_e32 v119, v109, v109
	v_fmac_f32_e32 v116, v62, v62
	v_fmac_f32_e32 v117, v78, v78
	v_fmac_f32_e32 v118, v94, v94
	v_fmac_f32_e32 v119, v110, v110
	v_fmac_f32_e32 v116, v63, v63
	v_fmac_f32_e32 v117, v79, v79
	v_fmac_f32_e32 v118, v95, v95
	v_fmac_f32_e32 v119, v111, v111
	v_fmac_f32_e32 v116, v64, v64
	v_fmac_f32_e32 v117, v80, v80
	v_fmac_f32_e32 v118, v96, v96
	v_fmac_f32_e32 v119, v112, v112
	v_fmac_f32_e32 v116, v65, v65
	v_fmac_f32_e32 v117, v81, v81
	v_fmac_f32_e32 v118, v97, v97
	v_fmac_f32_e32 v119, v113, v113
	v_fmac_f32_e32 v116, v66, v66
	v_fmac_f32_e32 v117, v82, v82
	v_fmac_f32_e32 v118, v98, v98
	v_fmac_f32_e32 v119, v114, v114
	v_fmac_f32_e32 v116, v67, v67
	v_fmac_f32_e32 v117, v83, v83
	v_fmac_f32_e32 v118, v99, v99
	v_fmac_f32_e32 v119, v115, v115
	v_add_f32_dpp v132, v116, v116 quad_perm:[1,0,3,2] row_mask:0xf bank_mask:0xf
	v_add_f32_dpp v133, v117, v117 quad_perm:[1,0,3,2] row_mask:0xf bank_mask:0xf
	v_add_f32_dpp v134, v118, v118 quad_perm:[1,0,3,2] row_mask:0xf bank_mask:0xf
	v_add_f32_dpp v135, v119, v119 quad_perm:[1,0,3,2] row_mask:0xf bank_mask:0xf
	v_add_f32_dpp v136, v132, v132 quad_perm:[2,3,0,1] row_mask:0xf bank_mask:0xf
	v_add_f32_dpp v137, v133, v133 quad_perm:[2,3,0,1] row_mask:0xf bank_mask:0xf
	v_add_f32_dpp v138, v134, v134 quad_perm:[2,3,0,1] row_mask:0xf bank_mask:0xf
	v_add_f32_dpp v139, v135, v135 quad_perm:[2,3,0,1] row_mask:0xf bank_mask:0xf
	v_add_f32_dpp v132, v136, v136 row_ror:4 row_mask:0xf bank_mask:0xf
	v_add_f32_dpp v133, v137, v137 row_ror:4 row_mask:0xf bank_mask:0xf
	v_add_f32_dpp v134, v138, v138 row_ror:4 row_mask:0xf bank_mask:0xf
	v_add_f32_dpp v135, v139, v139 row_ror:4 row_mask:0xf bank_mask:0xf
	v_add_f32_dpp v136, v132, v132 row_ror:8 row_mask:0xf bank_mask:0xf
	v_add_f32_dpp v137, v133, v133 row_ror:8 row_mask:0xf bank_mask:0xf
	v_add_f32_dpp v138, v134, v134 row_ror:8 row_mask:0xf bank_mask:0xf
	v_add_f32_dpp v139, v135, v135 row_ror:8 row_mask:0xf bank_mask:0xf
	s_nop 1
	v_readlane_b32 s16, v136, 0
	v_readlane_b32 s17, v136, 16
	v_readlane_b32 s18, v136, 32
	v_readlane_b32 s19, v136, 48
	v_readlane_b32 s20, v137, 0
	v_readlane_b32 s21, v137, 16
	v_readlane_b32 s22, v137, 32
	v_readlane_b32 s23, v137, 48
	v_readlane_b32 s24, v138, 0
	v_readlane_b32 s25, v138, 16
	v_readlane_b32 s26, v138, 32
	v_readlane_b32 s27, v138, 48
	v_readlane_b32 s28, v139, 0
	v_readlane_b32 s29, v139, 16
	v_readlane_b32 s30, v139, 32
	v_readlane_b32 s31, v139, 48
	s_nop 1
	v_mov_b32_e32 v132, s16
	v_mov_b32_e32 v133, s20
	v_mov_b32_e32 v134, s24
	v_mov_b32_e32 v135, s28
	v_add_f32_e32 v132, s17, v132
	v_add_f32_e32 v133, s21, v133
	v_add_f32_e32 v134, s25, v134
	v_add_f32_e32 v135, s29, v135
	v_add_f32_e32 v132, s18, v132
	v_add_f32_e32 v133, s22, v133
	v_add_f32_e32 v134, s26, v134
	v_add_f32_e32 v135, s30, v135
	v_add_f32_e32 v132, s19, v132
	v_add_f32_e32 v133, s23, v133
	v_add_f32_e32 v134, s27, v134
	v_add_f32_e32 v135, s31, v135
	v_fma_f32 v140, v132, v3, v121
	v_fma_f32 v141, v133, v3, v121
	v_fma_f32 v142, v134, v3, v121
	v_fma_f32 v143, v135, v3, v121
	v_rsq_f32_e32 v124, v140
	v_rsq_f32_e32 v126, v141
	v_rsq_f32_e32 v128, v142
	v_rsq_f32_e32 v130, v143
	s_nop 0
	v_mul_f32_e32 v132, v140, v124
	v_mul_f32_e32 v133, v141, v126
	v_mul_f32_e32 v134, v142, v128
	v_mul_f32_e32 v135, v143, v130
	v_mul_f32_e32 v132, v132, v124
	v_mul_f32_e32 v133, v133, v126
	v_mul_f32_e32 v134, v134, v128
	v_mul_f32_e32 v135, v135, v130
	v_sub_f32_e32 v132, 1.0, v132
	v_sub_f32_e32 v133, 1.0, v133
	v_sub_f32_e32 v134, 1.0, v134
	v_sub_f32_e32 v135, 1.0, v135
	v_mul_f32_e32 v136, 0.5, v124
	v_mul_f32_e32 v137, 0.5, v126
	v_mul_f32_e32 v138, 0.5, v128
	v_mul_f32_e32 v139, 0.5, v130
	v_fmac_f32_e32 v124, v136, v132
	v_fmac_f32_e32 v126, v137, v133
	v_fmac_f32_e32 v128, v138, v134
	v_fmac_f32_e32 v130, v139, v135
	v_pk_mul_f32 v[52:53], v[52:53], v[124:125] op_sel_hi:[1,0]
	v_pk_mul_f32 v[54:55], v[54:55], v[124:125] op_sel_hi:[1,0]
	v_pk_mul_f32 v[56:57], v[56:57], v[124:125] op_sel_hi:[1,0]
	v_pk_mul_f32 v[58:59], v[58:59], v[124:125] op_sel_hi:[1,0]
	v_pk_mul_f32 v[60:61], v[60:61], v[124:125] op_sel_hi:[1,0]
	v_pk_mul_f32 v[62:63], v[62:63], v[124:125] op_sel_hi:[1,0]
	v_pk_mul_f32 v[64:65], v[64:65], v[124:125] op_sel_hi:[1,0]
	v_pk_mul_f32 v[66:67], v[66:67], v[124:125] op_sel_hi:[1,0]
	v_pk_mul_f32 v[52:53], v[52:53], v[4:5]
	v_pk_mul_f32 v[54:55], v[54:55], v[6:7]
	v_pk_mul_f32 v[56:57], v[56:57], v[8:9]
	v_pk_mul_f32 v[58:59], v[58:59], v[10:11]
	v_pk_mul_f32 v[60:61], v[60:61], v[12:13]
	v_pk_mul_f32 v[62:63], v[62:63], v[14:15]
	v_pk_mul_f32 v[64:65], v[64:65], v[16:17]
	v_pk_mul_f32 v[66:67], v[66:67], v[18:19]
	global_store_dwordx4 v2, v[52:55], s[14:15] nt
	global_store_dwordx4 v2, v[56:59], s[14:15] offset:1024 nt
	global_store_dwordx4 v2, v[60:63], s[14:15] offset:2048 nt
	global_store_dwordx4 v2, v[64:67], s[14:15] offset:3072 nt
	v_pk_mul_f32 v[68:69], v[68:69], v[126:127] op_sel_hi:[1,0]
	v_pk_mul_f32 v[70:71], v[70:71], v[126:127] op_sel_hi:[1,0]
	v_pk_mul_f32 v[72:73], v[72:73], v[126:127] op_sel_hi:[1,0]
	v_pk_mul_f32 v[74:75], v[74:75], v[126:127] op_sel_hi:[1,0]
	v_pk_mul_f32 v[76:77], v[76:77], v[126:127] op_sel_hi:[1,0]
	v_pk_mul_f32 v[78:79], v[78:79], v[126:127] op_sel_hi:[1,0]
	v_pk_mul_f32 v[80:81], v[80:81], v[126:127] op_sel_hi:[1,0]
	v_pk_mul_f32 v[82:83], v[82:83], v[126:127] op_sel_hi:[1,0]
	v_pk_mul_f32 v[68:69], v[68:69], v[4:5]
	v_pk_mul_f32 v[70:71], v[70:71], v[6:7]
	v_pk_mul_f32 v[72:73], v[72:73], v[8:9]
	v_pk_mul_f32 v[74:75], v[74:75], v[10:11]
	v_pk_mul_f32 v[76:77], v[76:77], v[12:13]
	v_pk_mul_f32 v[78:79], v[78:79], v[14:15]
	v_pk_mul_f32 v[80:81], v[80:81], v[16:17]
	v_pk_mul_f32 v[82:83], v[82:83], v[18:19]
	s_add_u32 s2, s14, 0x1000
	s_addc_u32 s3, s15, 0
	global_store_dwordx4 v2, v[68:71], s[2:3] nt
	global_store_dwordx4 v2, v[72:75], s[2:3] offset:1024 nt
	global_store_dwordx4 v2, v[76:79], s[2:3] offset:2048 nt
	global_store_dwordx4 v2, v[80:83], s[2:3] offset:3072 nt
	v_pk_mul_f32 v[84:85], v[84:85], v[128:129] op_sel_hi:[1,0]
	v_pk_mul_f32 v[86:87], v[86:87], v[128:129] op_sel_hi:[1,0]
	v_pk_mul_f32 v[88:89], v[88:89], v[128:129] op_sel_hi:[1,0]
	v_pk_mul_f32 v[90:91], v[90:91], v[128:129] op_sel_hi:[1,0]
	v_pk_mul_f32 v[92:93], v[92:93], v[128:129] op_sel_hi:[1,0]
	v_pk_mul_f32 v[94:95], v[94:95], v[128:129] op_sel_hi:[1,0]
	v_pk_mul_f32 v[96:97], v[96:97], v[128:129] op_sel_hi:[1,0]
	v_pk_mul_f32 v[98:99], v[98:99], v[128:129] op_sel_hi:[1,0]
	v_pk_mul_f32 v[84:85], v[84:85], v[4:5]
	v_pk_mul_f32 v[86:87], v[86:87], v[6:7]
	v_pk_mul_f32 v[88:89], v[88:89], v[8:9]
	v_pk_mul_f32 v[90:91], v[90:91], v[10:11]
	v_pk_mul_f32 v[92:93], v[92:93], v[12:13]
	v_pk_mul_f32 v[94:95], v[94:95], v[14:15]
	v_pk_mul_f32 v[96:97], v[96:97], v[16:17]
	v_pk_mul_f32 v[98:99], v[98:99], v[18:19]
	s_add_u32 s2, s14, 0x2000
	s_addc_u32 s3, s15, 0
	global_store_dwordx4 v2, v[84:87], s[2:3] nt
	global_store_dwordx4 v2, v[88:91], s[2:3] offset:1024 nt
	global_store_dwordx4 v2, v[92:95], s[2:3] offset:2048 nt
	global_store_dwordx4 v2, v[96:99], s[2:3] offset:3072 nt
	v_pk_mul_f32 v[100:101], v[100:101], v[130:131] op_sel_hi:[1,0]
	v_pk_mul_f32 v[102:103], v[102:103], v[130:131] op_sel_hi:[1,0]
	v_pk_mul_f32 v[104:105], v[104:105], v[130:131] op_sel_hi:[1,0]
	v_pk_mul_f32 v[106:107], v[106:107], v[130:131] op_sel_hi:[1,0]
	v_pk_mul_f32 v[108:109], v[108:109], v[130:131] op_sel_hi:[1,0]
	v_pk_mul_f32 v[110:111], v[110:111], v[130:131] op_sel_hi:[1,0]
	v_pk_mul_f32 v[112:113], v[112:113], v[130:131] op_sel_hi:[1,0]
	v_pk_mul_f32 v[114:115], v[114:115], v[130:131] op_sel_hi:[1,0]
	v_pk_mul_f32 v[100:101], v[100:101], v[4:5]
	v_pk_mul_f32 v[102:103], v[102:103], v[6:7]
	v_pk_mul_f32 v[104:105], v[104:105], v[8:9]
	v_pk_mul_f32 v[106:107], v[106:107], v[10:11]
	v_pk_mul_f32 v[108:109], v[108:109], v[12:13]
	v_pk_mul_f32 v[110:111], v[110:111], v[14:15]
	v_pk_mul_f32 v[112:113], v[112:113], v[16:17]
	v_pk_mul_f32 v[114:115], v[114:115], v[18:19]
	s_add_u32 s2, s14, 0x3000
	s_addc_u32 s3, s15, 0
	global_store_dwordx4 v2, v[100:103], s[2:3] nt
	global_store_dwordx4 v2, v[104:107], s[2:3] offset:1024 nt
	global_store_dwordx4 v2, v[108:111], s[2:3] offset:2048 nt
	global_store_dwordx4 v2, v[112:115], s[2:3] offset:3072 nt
	s_add_u32 s12, s12, 0x2000
	s_addc_u32 s13, s13, 0
	s_add_u32 s14, s14, 0x4000
	s_addc_u32 s15, s15, 0
	s_add_i32 s10, s10, -1
	s_cmp_lg_u32 s10, 0
	s_cbranch_scc1 .Lp10a_loop
